# row-max exchange via v_permlane32_swap instead of ds_bpermute (no LDS round trip on the softmax serial path), plus zero-hide and loop-edge edits combined
# baseline (speedup 1.0000x reference)
; __device__ __forceinline__ void compute_a(LAS unsigned char* lds, const UD& x, const bf16x8 (&qr)[4], int wid, int lane, u32x4 (&pw)[10], float& mx_o, float& l_o) {
;     ...
;     float mx = s[2][0];
; #pragma unroll
;     for (int ht = 0; ht < 5; ++ht)
; #pragma unroll
;         for (int r = 0; r < 16; ++r) mx = fmaxf(mx, s[ht][r]);
;     mx = fmaxf(mx, __shfl_xor(mx, 32));
;     float lsum = 0.f;
; #pragma unroll
;     for (int ht = 0; ht < 5; ++ht)
; #pragma unroll
;         for (int r = 0; r < 16; ++r) { const float p = __builtin_amdgcn_exp2f(s[ht][r] - mx); s[ht][r] = p; lsum += p; }
;     lsum += __shfl_xor(lsum, 32);
.LBB0_644:
	v_max3_f32 v56, v16, v133, v149
	v_max3_f32 v56, v56, v233, v234
	v_max3_f32 v56, v56, v147, v137
	v_max3_f32 v56, v56, v135, v134
	v_max3_f32 v56, v56, v132, v83
	v_max3_f32 v56, v56, v82, v80
	v_max3_f32 v56, v56, v76, v75
	v_max3_f32 v56, v56, v74, v73
	v_max3_f32 v56, v56, v32, v33
	v_max3_f32 v56, v56, v34, v35
	v_max3_f32 v56, v56, v36, v37
	v_max3_f32 v56, v56, v38, v39
	v_max3_f32 v56, v56, v40, v41
	v_max3_f32 v56, v56, v42, v43
	v_max3_f32 v56, v56, v44, v45
	v_max3_f32 v56, v56, v46, v47
	v_max3_f32 v56, v56, v16, v17
	v_max3_f32 v56, v56, v18, v19
	v_max3_f32 v56, v56, v20, v21
	v_max3_f32 v56, v56, v22, v23
	v_max3_f32 v56, v56, v24, v25
	v_max3_f32 v56, v56, v26, v27
	v_max3_f32 v56, v56, v28, v29
	v_max3_f32 v56, v56, v30, v31
	v_max3_f32 v56, v56, v0, v1
	v_max3_f32 v56, v56, v2, v3
	v_max3_f32 v56, v56, v4, v5
	v_max3_f32 v56, v56, v6, v7
	v_max3_f32 v56, v56, v8, v9
	v_max3_f32 v56, v56, v10, v11
	v_max3_f32 v56, v56, v12, v13
	v_max3_f32 v56, v56, v14, v15
	v_max3_f32 v56, v56, v69, v70
	v_max3_f32 v56, v56, v71, v72
	v_max3_f32 v56, v56, v67, v66
	v_max3_f32 v56, v56, v65, v64
	v_max3_f32 v56, v56, v55, v54
	v_max3_f32 v56, v56, v53, v52
	v_max3_f32 v56, v56, v51, v50
	v_max3_f32 v56, v56, v49, v48
	v_mov_b32_e32 v57, v56
	v_mov_b32_e32 v58, v56
	s_nop 1
	v_permlane32_swap_b32_e32 v57, v58
	s_add_i32 s1, s18, 32
	v_readlane_b32 s4, v253, 39
	s_cmp_ge_i32 s18, s4
	s_cselect_b64 s[46:47], -1, 0
	s_waitcnt lgkmcnt(0)
	s_nop 0
	v_max_f32_e32 v68, v57, v58
	v_sub_f32_e32 v56, v133, v68
	v_sub_f32_e32 v57, v149, v68
	v_exp_f32_e32 v56, v56
	v_sub_f32_e32 v58, v233, v68
	v_exp_f32_e32 v57, v57
	v_sub_f32_e32 v59, v234, v68
	v_exp_f32_e32 v58, v58
	v_sub_f32_e32 v60, v147, v68
	v_exp_f32_e32 v59, v59
	v_add_f32_e32 v61, 0, v56
	v_exp_f32_e32 v60, v60
	v_sub_f32_e32 v62, v137, v68
	v_add_f32_e32 v61, v57, v61
	v_exp_f32_e32 v62, v62
	v_sub_f32_e32 v63, v135, v68
	v_add_f32_e32 v61, v58, v61
	v_exp_f32_e32 v63, v63
	v_sub_f32_e32 v77, v134, v68
	v_add_f32_e32 v61, v59, v61
	v_exp_f32_e32 v77, v77
	v_sub_f32_e32 v78, v132, v68
	v_add_f32_e32 v61, v60, v61
	v_exp_f32_e32 v78, v78
	v_sub_f32_e32 v79, v83, v68
	v_add_f32_e32 v61, v62, v61
	v_exp_f32_e32 v79, v79
	v_sub_f32_e32 v82, v82, v68
	v_add_f32_e32 v61, v63, v61
	v_exp_f32_e32 v82, v82
	v_sub_f32_e32 v80, v80, v68
	v_add_f32_e32 v61, v77, v61
	v_exp_f32_e32 v80, v80
	v_sub_f32_e32 v76, v76, v68
	v_add_f32_e32 v61, v78, v61
	v_exp_f32_e32 v76, v76
	v_sub_f32_e32 v75, v75, v68
	v_add_f32_e32 v61, v79, v61
	v_exp_f32_e32 v75, v75
	v_sub_f32_e32 v74, v74, v68
	v_add_f32_e32 v61, v82, v61
	v_exp_f32_e32 v74, v74
	v_sub_f32_e32 v73, v73, v68
	v_add_f32_e32 v61, v80, v61
	v_exp_f32_e32 v73, v73
	v_sub_f32_e32 v32, v32, v68
	v_add_f32_e32 v61, v76, v61
	v_exp_f32_e32 v32, v32
	v_sub_f32_e32 v33, v33, v68
	v_add_f32_e32 v61, v75, v61
	v_exp_f32_e32 v33, v33
	v_sub_f32_e32 v34, v34, v68
	v_add_f32_e32 v61, v74, v61
	v_exp_f32_e32 v34, v34
	v_sub_f32_e32 v35, v35, v68
	v_add_f32_e32 v61, v73, v61
	v_exp_f32_e32 v35, v35
	v_sub_f32_e32 v36, v36, v68
	v_add_f32_e32 v61, v32, v61
	v_exp_f32_e32 v36, v36
	v_sub_f32_e32 v37, v37, v68
	v_add_f32_e32 v61, v33, v61
	v_exp_f32_e32 v37, v37
	v_sub_f32_e32 v38, v38, v68
	v_add_f32_e32 v61, v34, v61
	v_exp_f32_e32 v38, v38
	v_sub_f32_e32 v39, v39, v68
	v_add_f32_e32 v61, v35, v61
	v_exp_f32_e32 v39, v39
	v_sub_f32_e32 v40, v40, v68
	v_add_f32_e32 v61, v36, v61
	v_exp_f32_e32 v40, v40
	v_sub_f32_e32 v41, v41, v68
	v_add_f32_e32 v61, v37, v61
	v_exp_f32_e32 v41, v41
	v_sub_f32_e32 v42, v42, v68
	v_add_f32_e32 v61, v38, v61
	v_exp_f32_e32 v42, v42
	v_sub_f32_e32 v43, v43, v68
	v_add_f32_e32 v61, v39, v61
	v_exp_f32_e32 v43, v43
	v_sub_f32_e32 v44, v44, v68
	v_add_f32_e32 v61, v40, v61
	v_exp_f32_e32 v44, v44
	v_sub_f32_e32 v45, v45, v68
	v_add_f32_e32 v61, v41, v61
	v_exp_f32_e32 v45, v45
	v_sub_f32_e32 v46, v46, v68
	v_add_f32_e32 v61, v42, v61
	v_exp_f32_e32 v46, v46
	v_sub_f32_e32 v47, v47, v68
	v_add_f32_e32 v61, v43, v61
	v_exp_f32_e32 v47, v47
	v_sub_f32_e32 v16, v16, v68
	v_add_f32_e32 v61, v44, v61
	v_exp_f32_e32 v83, v16
	v_sub_f32_e32 v16, v17, v68
	v_add_f32_e32 v61, v45, v61
	v_exp_f32_e32 v132, v16
	v_sub_f32_e32 v16, v18, v68
	v_add_f32_e32 v61, v46, v61
	v_exp_f32_e32 v133, v16
	v_sub_f32_e32 v16, v19, v68
	v_add_f32_e32 v61, v47, v61
	v_exp_f32_e32 v134, v16
	v_sub_f32_e32 v17, v20, v68
	v_add_f32_e32 v16, v83, v61
	v_exp_f32_e32 v20, v17
	v_sub_f32_e32 v17, v21, v68
	v_add_f32_e32 v16, v132, v16
	v_exp_f32_e32 v21, v17
	v_sub_f32_e32 v17, v22, v68
	v_add_f32_e32 v16, v133, v16
	v_exp_f32_e32 v22, v17
	v_sub_f32_e32 v17, v23, v68
	v_add_f32_e32 v16, v134, v16
	v_exp_f32_e32 v23, v17
	v_sub_f32_e32 v17, v24, v68
	v_add_f32_e32 v16, v20, v16
	v_exp_f32_e32 v24, v17
	v_sub_f32_e32 v17, v25, v68
	v_add_f32_e32 v16, v21, v16
	v_exp_f32_e32 v25, v17
	v_sub_f32_e32 v17, v26, v68
	v_add_f32_e32 v16, v22, v16
	v_exp_f32_e32 v26, v17
	v_sub_f32_e32 v17, v27, v68
	v_add_f32_e32 v16, v23, v16
	v_exp_f32_e32 v27, v17
	v_sub_f32_e32 v17, v28, v68
	v_add_f32_e32 v16, v24, v16
	v_exp_f32_e32 v28, v17
	v_sub_f32_e32 v17, v29, v68
	v_add_f32_e32 v16, v25, v16
	v_exp_f32_e32 v29, v17
	v_sub_f32_e32 v17, v30, v68
	v_add_f32_e32 v16, v26, v16
; __device__ __forceinline__ unsigned cvt_pk_bf16(float lo, float hi) { unsigned r; asm volatile("v_cvt_pk_bf16_f32 %0, %1, %2" : "=v"(r) : "v"(lo), "v"(hi)); return r; }
; __device__ __forceinline__ void load_kv(u32x4 (&val)[14], const UD& x, const unsigned char* ws, int tid) {
;     const int br = x.br, u = x.u, sub = tid & 15, s0 = tid >> 4;
;     const bf16_t* base = (const bf16_t*)(ws + ((sub < 8) ? off_k(x.b) : off_v(x.b))) + (size_t)x.b * SEQ * AW + x.h * HD + (sub & 7) * 8;
;     if (br < 2) {
;         const int d = (br == 0) ? 1 : 4, L = SEQ / d, T0 = (br == 0) ? 256 * u : 256 * (u & 1), cls = (br == 0) ? 0 : (u >> 1);
;         const int k0 = T0 - 64 + s0;
;         const bf16_t* p0 = base + ((long)k0 * d + cls) * AW; const long stride = (long)32 * d * AW;
; #pragma unroll
;         for (int i = 0; i < 14; ++i) { const int key = k0 + 32 * i; val[i] = (u32x4){0u, 0u, 0u, 0u};
;             if ((i < 12) && (key >= 0) && (key < L)) val[i] = *(const u32x4*)(p0 + i * stride); }
; __device__ __forceinline__ void compute_a(LAS unsigned char* lds, const UD& x, const bf16x8 (&qr)[4], int wid, int lane, u32x4 (&pw)[10], float& mx_o, float& l_o) {
;     ...
;         for (int r = 0; r < 16; ++r) { const float p = __builtin_amdgcn_exp2f(s[ht][r] - mx); s[ht][r] = p; lsum += p; }
;     lsum += __shfl_xor(lsum, 32);
; #pragma unroll
;     for (int g = 0; g < 10; ++g) {
;         const int ht = g >> 1, rb = (g & 1) * 8;
;         pw[g].x = pg8::cvt_pk_bf16(s[ht][rb + 0], s[ht][rb + 1]); pw[g].y = pg8::cvt_pk_bf16(s[ht][rb + 2], s[ht][rb + 3]); pw[g].z = pg8::cvt_pk_bf16(s[ht][rb + 4], s[ht][rb + 5]); pw[g].w = pg8::cvt_pk_bf16(s[ht][rb + 6], s[ht][rb + 7]);
;     }
	v_exp_f32_e32 v30, v17
	v_sub_f32_e32 v17, v31, v68
	v_add_f32_e32 v16, v27, v16
	v_exp_f32_e32 v31, v17
	v_sub_f32_e32 v0, v0, v68
	v_add_f32_e32 v16, v28, v16
	v_exp_f32_e32 v0, v0
	v_sub_f32_e32 v1, v1, v68
	v_add_f32_e32 v16, v29, v16
	v_exp_f32_e32 v1, v1
	v_sub_f32_e32 v2, v2, v68
	v_add_f32_e32 v16, v30, v16
	v_exp_f32_e32 v2, v2
	v_sub_f32_e32 v3, v3, v68
	v_add_f32_e32 v16, v31, v16
	v_exp_f32_e32 v3, v3
	v_sub_f32_e32 v4, v4, v68
	v_add_f32_e32 v16, v0, v16
	v_exp_f32_e32 v4, v4
	v_sub_f32_e32 v5, v5, v68
	v_add_f32_e32 v16, v1, v16
	v_exp_f32_e32 v5, v5
	v_sub_f32_e32 v6, v6, v68
	v_add_f32_e32 v16, v2, v16
	v_exp_f32_e32 v6, v6
	v_sub_f32_e32 v7, v7, v68
	v_add_f32_e32 v16, v3, v16
	v_exp_f32_e32 v7, v7
	v_sub_f32_e32 v8, v8, v68
	v_add_f32_e32 v16, v4, v16
	v_exp_f32_e32 v8, v8
	v_sub_f32_e32 v9, v9, v68
	v_add_f32_e32 v16, v5, v16
	v_exp_f32_e32 v9, v9
	v_sub_f32_e32 v10, v10, v68
	v_add_f32_e32 v16, v6, v16
	v_exp_f32_e32 v10, v10
	v_sub_f32_e32 v11, v11, v68
	v_add_f32_e32 v16, v7, v16
	v_exp_f32_e32 v11, v11
	v_sub_f32_e32 v12, v12, v68
	v_add_f32_e32 v16, v8, v16
	v_exp_f32_e32 v12, v12
	v_sub_f32_e32 v13, v13, v68
	v_add_f32_e32 v16, v9, v16
	v_exp_f32_e32 v13, v13
	v_sub_f32_e32 v14, v14, v68
	v_add_f32_e32 v16, v10, v16
	v_exp_f32_e32 v14, v14
	v_sub_f32_e32 v15, v15, v68
	v_add_f32_e32 v16, v11, v16
	v_exp_f32_e32 v15, v15
	v_sub_f32_e32 v17, v69, v68
	v_add_f32_e32 v16, v12, v16
	v_exp_f32_e32 v135, v17
	v_sub_f32_e32 v17, v70, v68
	v_add_f32_e32 v16, v13, v16
	v_exp_f32_e32 v70, v17
	v_sub_f32_e32 v17, v71, v68
	v_add_f32_e32 v16, v14, v16
	v_exp_f32_e32 v71, v17
	v_sub_f32_e32 v17, v72, v68
	v_add_f32_e32 v16, v15, v16
	v_exp_f32_e32 v72, v17
	v_sub_f32_e32 v17, v67, v68
	v_add_f32_e32 v16, v135, v16
	v_exp_f32_e32 v137, v17
	v_sub_f32_e32 v17, v66, v68
	v_add_f32_e32 v16, v70, v16
	v_exp_f32_e32 v147, v17
	v_sub_f32_e32 v17, v65, v68
	v_add_f32_e32 v16, v71, v16
	v_exp_f32_e32 v149, v17
	v_sub_f32_e32 v17, v64, v68
	v_add_f32_e32 v16, v72, v16
	v_exp_f32_e32 v196, v17
	v_sub_f32_e32 v17, v55, v68
	v_add_f32_e32 v16, v137, v16
	v_exp_f32_e32 v197, v17
	v_sub_f32_e32 v17, v54, v68
	v_add_f32_e32 v16, v147, v16
	v_exp_f32_e32 v198, v17
	v_sub_f32_e32 v17, v53, v68
	v_add_f32_e32 v16, v149, v16
	v_exp_f32_e32 v199, v17
	v_sub_f32_e32 v17, v52, v68
	v_add_f32_e32 v16, v196, v16
	v_exp_f32_e32 v233, v17
	v_sub_f32_e32 v17, v51, v68
	v_add_f32_e32 v16, v197, v16
	v_exp_f32_e32 v234, v17
	v_sub_f32_e32 v17, v50, v68
	v_add_f32_e32 v16, v198, v16
	v_exp_f32_e32 v235, v17
	v_sub_f32_e32 v17, v49, v68
	v_add_f32_e32 v16, v199, v16
	v_exp_f32_e32 v236, v17
	v_sub_f32_e32 v17, v48, v68
	v_add_f32_e32 v16, v233, v16
	v_exp_f32_e32 v237, v17
	v_add_f32_e32 v16, v234, v16
	v_add_f32_e32 v16, v235, v16
	v_add_f32_e32 v16, v236, v16
	v_add_f32_e32 v69, v237, v16
	v_cvt_pk_bf16_f32 v16, v56, v57
	v_cvt_pk_bf16_f32 v17, v58, v59
	v_cvt_pk_bf16_f32 v18, v60, v62
	v_cvt_pk_bf16_f32 v19, v63, v77
	v_cvt_pk_bf16_f32 v64, v78, v79
	v_cvt_pk_bf16_f32 v65, v82, v80
	v_cvt_pk_bf16_f32 v66, v76, v75
	v_cvt_pk_bf16_f32 v67, v74, v73
	v_cvt_pk_bf16_f32 v60, v32, v33
	v_cvt_pk_bf16_f32 v61, v34, v35
	v_cvt_pk_bf16_f32 v62, v36, v37
	v_cvt_pk_bf16_f32 v63, v38, v39
	v_cvt_pk_bf16_f32 v56, v40, v41
	v_cvt_pk_bf16_f32 v57, v42, v43
	v_cvt_pk_bf16_f32 v58, v44, v45
	v_cvt_pk_bf16_f32 v59, v46, v47
	v_cvt_pk_bf16_f32 v52, v83, v132
	v_cvt_pk_bf16_f32 v53, v133, v134
	v_cvt_pk_bf16_f32 v54, v20, v21
	v_cvt_pk_bf16_f32 v55, v22, v23
	v_cvt_pk_bf16_f32 v48, v24, v25
	v_cvt_pk_bf16_f32 v49, v26, v27
	v_cvt_pk_bf16_f32 v50, v28, v29
	v_cvt_pk_bf16_f32 v51, v30, v31
	v_cvt_pk_bf16_f32 v44, v0, v1
	v_cvt_pk_bf16_f32 v45, v2, v3
	v_cvt_pk_bf16_f32 v46, v4, v5
	v_cvt_pk_bf16_f32 v47, v6, v7
	v_cvt_pk_bf16_f32 v40, v8, v9
	v_cvt_pk_bf16_f32 v41, v10, v11
	v_cvt_pk_bf16_f32 v42, v12, v13
	v_cvt_pk_bf16_f32 v43, v14, v15
	v_cvt_pk_bf16_f32 v36, v135, v70
	ds_bpermute_b32 v70, v162, v69
	s_and_b64 vcc, exec, s[46:47]
	v_cvt_pk_bf16_f32 v37, v71, v72
	v_cvt_pk_bf16_f32 v38, v137, v147
	v_cvt_pk_bf16_f32 v39, v149, v196
	v_cvt_pk_bf16_f32 v32, v197, v198
	v_cvt_pk_bf16_f32 v33, v199, v233
	v_cvt_pk_bf16_f32 v34, v234, v235
	v_cvt_pk_bf16_f32 v35, v236, v237
	s_cbranch_vccnz .LBB0_689
	s_ashr_i32 s4, s1, 4
	s_mul_hi_i32 s5, s4, 0x2aaaaaab
	s_lshr_b32 s19, s5, 31
	s_ashr_i32 s5, s5, 1
	s_add_i32 vcc_lo, s5, s19
	s_mul_i32 s5, vcc_lo, 12
	s_ashr_i32 vcc_hi, vcc_lo, 31
	s_sub_i32 s19, s4, s5
	s_lshl_b64 s[4:5], vcc, 23
	v_lshl_add_u64 v[0:1], v[138:139], 0, s[4:5]
	v_mad_i64_i32 v[0:1], s[4:5], vcc_lo, v200, v[0:1]
	s_lshl_b32 s4, s19, 6
	s_ashr_i32 s5, s4, 31
	v_lshl_add_u64 v[0:1], s[4:5], 1, v[0:1]
	v_mov_b32_e32 v137, v81
	v_lshl_add_u64 v[0:1], v[0:1], 0, v[136:137]
	s_bitcmp1_b32 s18, 3
	s_mov_b64 vcc, -1
	s_cbranch_scc0 .LBB0_663
	v_mov_b32_e32 v88, v81
	v_mov_b32_e32 v89, v81
	v_mov_b32_e32 v90, v81
	v_mov_b32_e32 v91, v81
	v_mov_b64_e32 v[84:85], v[88:89]
	v_lshl_add_u64 v[2:3], v[0:1], 0, v[140:141]
	v_mov_b64_e32 v[86:87], v[90:91]
	s_mov_b64 s[18:19], exec
	v_readlane_b32 s4, v255, 18
	v_readlane_b32 s5, v255, 19
	s_and_b64 s[4:5], s[18:19], s[4:5]
	s_mov_b64 exec, s[4:5]
	s_cbranch_execz .LBB0_648
	global_load_dwordx4 v[84:87], v[2:3], off

; __device__ __forceinline__ void compute_a(LAS unsigned char* lds, const UD& x, const bf16x8 (&qr)[4], int wid, int lane, u32x4 (&pw)[10], float& mx_o, float& l_o) {
;     ...
;     float mx = s[2][0];
; #pragma unroll
;     for (int ht = 0; ht < 5; ++ht)
; #pragma unroll
;         for (int r = 0; r < 16; ++r) mx = fmaxf(mx, s[ht][r]);
;     mx = fmaxf(mx, __shfl_xor(mx, 32));
;     float lsum = 0.f;
; #pragma unroll
;     for (int ht = 0; ht < 5; ++ht)
; #pragma unroll
;         for (int r = 0; r < 16; ++r) { const float p = __builtin_amdgcn_exp2f(s[ht][r] - mx); s[ht][r] = p; lsum += p; }
;     lsum += __shfl_xor(lsum, 32);
.LBB0_754:
	v_max3_f32 v56, v16, v133, v149
	v_max3_f32 v56, v56, v151, v229
	v_max3_f32 v56, v56, v230, v139
	v_max3_f32 v56, v56, v135, v134
	v_max3_f32 v56, v56, v132, v83
	v_max3_f32 v56, v56, v82, v80
	v_max3_f32 v56, v56, v76, v75
	v_max3_f32 v56, v56, v74, v73
	v_max3_f32 v56, v56, v32, v33
	v_max3_f32 v56, v56, v34, v35
	v_max3_f32 v56, v56, v36, v37
	v_max3_f32 v56, v56, v38, v39
	v_max3_f32 v56, v56, v40, v41
	v_max3_f32 v56, v56, v42, v43
	v_max3_f32 v56, v56, v44, v45
	v_max3_f32 v56, v56, v46, v47
	v_max3_f32 v56, v56, v16, v17
	v_max3_f32 v56, v56, v18, v19
	v_max3_f32 v56, v56, v20, v21
	v_max3_f32 v56, v56, v22, v23
	v_max3_f32 v56, v56, v24, v25
	v_max3_f32 v56, v56, v26, v27
	v_max3_f32 v56, v56, v28, v29
	v_max3_f32 v56, v56, v30, v31
	v_max3_f32 v56, v56, v0, v1
	v_max3_f32 v56, v56, v2, v3
	v_max3_f32 v56, v56, v4, v5
	v_max3_f32 v56, v56, v6, v7
	v_max3_f32 v56, v56, v8, v9
	v_max3_f32 v56, v56, v10, v11
	v_max3_f32 v56, v56, v12, v13
	v_max3_f32 v56, v56, v14, v15
	v_max3_f32 v56, v56, v69, v70
	v_max3_f32 v56, v56, v71, v72
	v_max3_f32 v56, v56, v67, v66
	v_max3_f32 v56, v56, v65, v64
	v_max3_f32 v56, v56, v55, v54
	v_max3_f32 v56, v56, v53, v52
	v_max3_f32 v56, v56, v51, v50
	v_max3_f32 v56, v56, v49, v48
	v_mov_b32_e32 v57, v56
	v_mov_b32_e32 v58, v56
	s_nop 1
	v_permlane32_swap_b32_e32 v57, v58
	s_add_i32 s14, s14, s72
	s_cmpk_gt_i32 s14, 0x5ff
	s_cselect_b64 s[46:47], -1, 0
	s_and_b64 vcc, exec, s[46:47]
	s_waitcnt lgkmcnt(0)
	s_nop 0
	v_max_f32_e32 v68, v57, v58
	v_sub_f32_e32 v56, v133, v68
	v_sub_f32_e32 v57, v149, v68
	v_exp_f32_e32 v56, v56
	v_sub_f32_e32 v58, v151, v68
	v_exp_f32_e32 v57, v57
	v_sub_f32_e32 v59, v229, v68
	v_exp_f32_e32 v58, v58
	v_sub_f32_e32 v60, v230, v68
	v_exp_f32_e32 v59, v59
	v_add_f32_e32 v61, 0, v56
	v_exp_f32_e32 v60, v60
	v_sub_f32_e32 v62, v139, v68
	v_add_f32_e32 v61, v57, v61
	v_exp_f32_e32 v62, v62
	v_sub_f32_e32 v63, v135, v68
	v_add_f32_e32 v61, v58, v61
	v_exp_f32_e32 v63, v63
	v_sub_f32_e32 v77, v134, v68
	v_add_f32_e32 v61, v59, v61
	v_exp_f32_e32 v77, v77
	v_sub_f32_e32 v78, v132, v68
	v_add_f32_e32 v61, v60, v61
	v_exp_f32_e32 v78, v78
	v_sub_f32_e32 v79, v83, v68
	v_add_f32_e32 v61, v62, v61
	v_exp_f32_e32 v79, v79
	v_sub_f32_e32 v82, v82, v68
	v_add_f32_e32 v61, v63, v61
	v_exp_f32_e32 v82, v82
	v_sub_f32_e32 v80, v80, v68
	v_add_f32_e32 v61, v77, v61
	v_exp_f32_e32 v80, v80
	v_sub_f32_e32 v76, v76, v68
	v_add_f32_e32 v61, v78, v61
	v_exp_f32_e32 v76, v76
	v_sub_f32_e32 v75, v75, v68
	v_add_f32_e32 v61, v79, v61
	v_exp_f32_e32 v75, v75
	v_sub_f32_e32 v74, v74, v68
	v_add_f32_e32 v61, v82, v61
	v_exp_f32_e32 v74, v74
	v_sub_f32_e32 v73, v73, v68
	v_add_f32_e32 v61, v80, v61
	v_exp_f32_e32 v73, v73
	v_sub_f32_e32 v32, v32, v68
	v_add_f32_e32 v61, v76, v61
	v_exp_f32_e32 v32, v32
	v_sub_f32_e32 v33, v33, v68
	v_add_f32_e32 v61, v75, v61
	v_exp_f32_e32 v33, v33
	v_sub_f32_e32 v34, v34, v68
	v_add_f32_e32 v61, v74, v61
	v_exp_f32_e32 v34, v34
	v_sub_f32_e32 v35, v35, v68
	v_add_f32_e32 v61, v73, v61
	v_exp_f32_e32 v35, v35
	v_sub_f32_e32 v36, v36, v68
	v_add_f32_e32 v61, v32, v61
	v_exp_f32_e32 v36, v36
	v_sub_f32_e32 v37, v37, v68
	v_add_f32_e32 v61, v33, v61
	v_exp_f32_e32 v37, v37
	v_sub_f32_e32 v38, v38, v68
	v_add_f32_e32 v61, v34, v61
	v_exp_f32_e32 v38, v38
	v_sub_f32_e32 v39, v39, v68
	v_add_f32_e32 v61, v35, v61
	v_exp_f32_e32 v39, v39
	v_sub_f32_e32 v40, v40, v68
	v_add_f32_e32 v61, v36, v61
	v_exp_f32_e32 v40, v40
	v_sub_f32_e32 v41, v41, v68
	v_add_f32_e32 v61, v37, v61
	v_exp_f32_e32 v41, v41
	v_sub_f32_e32 v42, v42, v68
	v_add_f32_e32 v61, v38, v61
	v_exp_f32_e32 v42, v42
	v_sub_f32_e32 v43, v43, v68
	v_add_f32_e32 v61, v39, v61
	v_exp_f32_e32 v43, v43
	v_sub_f32_e32 v44, v44, v68
	v_add_f32_e32 v61, v40, v61
	v_exp_f32_e32 v44, v44
	v_sub_f32_e32 v45, v45, v68
	v_add_f32_e32 v61, v41, v61
	v_exp_f32_e32 v45, v45
	v_sub_f32_e32 v46, v46, v68
	v_add_f32_e32 v61, v42, v61
	v_exp_f32_e32 v46, v46
	v_sub_f32_e32 v47, v47, v68
	v_add_f32_e32 v61, v43, v61
	v_exp_f32_e32 v47, v47
	v_sub_f32_e32 v16, v16, v68
	v_add_f32_e32 v61, v44, v61
	v_exp_f32_e32 v83, v16
	v_sub_f32_e32 v16, v17, v68
	v_add_f32_e32 v61, v45, v61
	v_exp_f32_e32 v132, v16
	v_sub_f32_e32 v16, v18, v68
	v_add_f32_e32 v61, v46, v61
	v_exp_f32_e32 v133, v16
	v_sub_f32_e32 v16, v19, v68
	v_add_f32_e32 v61, v47, v61
	v_exp_f32_e32 v134, v16
	v_sub_f32_e32 v17, v20, v68
	v_add_f32_e32 v16, v83, v61
	v_exp_f32_e32 v20, v17
	v_sub_f32_e32 v17, v21, v68
	v_add_f32_e32 v16, v132, v16
	v_exp_f32_e32 v21, v17
	v_sub_f32_e32 v17, v22, v68
	v_add_f32_e32 v16, v133, v16
	v_exp_f32_e32 v22, v17
	v_sub_f32_e32 v17, v23, v68
	v_add_f32_e32 v16, v134, v16
	v_exp_f32_e32 v23, v17
	v_sub_f32_e32 v17, v24, v68
	v_add_f32_e32 v16, v20, v16
	v_exp_f32_e32 v24, v17
	v_sub_f32_e32 v17, v25, v68
	v_add_f32_e32 v16, v21, v16
	v_exp_f32_e32 v25, v17
	v_sub_f32_e32 v17, v26, v68
	v_add_f32_e32 v16, v22, v16
	v_exp_f32_e32 v26, v17
	v_sub_f32_e32 v17, v27, v68
	v_add_f32_e32 v16, v23, v16
	v_exp_f32_e32 v27, v17
	v_sub_f32_e32 v17, v28, v68
	v_add_f32_e32 v16, v24, v16
	v_exp_f32_e32 v28, v17
	v_sub_f32_e32 v17, v29, v68
	v_add_f32_e32 v16, v25, v16
	v_exp_f32_e32 v29, v17
	v_sub_f32_e32 v17, v30, v68
	v_add_f32_e32 v16, v26, v16
; __device__ __forceinline__ unsigned cvt_pk_bf16(float lo, float hi) { unsigned r; asm volatile("v_cvt_pk_bf16_f32 %0, %1, %2" : "=v"(r) : "v"(lo), "v"(hi)); return r; }
; __device__ __forceinline__ void load_kv(u32x4 (&val)[14], const UD& x, const unsigned char* ws, int tid) {
;     const int br = x.br, u = x.u, sub = tid & 15, s0 = tid >> 4;
;     const bf16_t* base = (const bf16_t*)(ws + ((sub < 8) ? off_k(x.b) : off_v(x.b))) + (size_t)x.b * SEQ * AW + x.h * HD + (sub & 7) * 8;
;     if (br < 2) {
;         const int d = (br == 0) ? 1 : 4, L = SEQ / d, T0 = (br == 0) ? 256 * u : 256 * (u & 1), cls = (br == 0) ? 0 : (u >> 1);
;         const int k0 = T0 - 64 + s0;
;         const bf16_t* p0 = base + ((long)k0 * d + cls) * AW; const long stride = (long)32 * d * AW;
; #pragma unroll
;         for (int i = 0; i < 14; ++i) { const int key = k0 + 32 * i; val[i] = (u32x4){0u, 0u, 0u, 0u};
;             if ((i < 12) && (key >= 0) && (key < L)) val[i] = *(const u32x4*)(p0 + i * stride); }
;     } else {
;         const bf16_t* pa = base + ((long)(s0 - 64) * 16 + 2 * u) * AW; const bf16_t* pb = base + ((long)s0 * 16 + 2 * u + 1) * AW; const long stride = (long)32 * 16 * AW;
; #pragma unroll
;         for (int i = 0; i < 14; ++i) { val[i] = (u32x4){0u, 0u, 0u, 0u};
;             if (i < 8) { const int key = s0 + 32 * i - 64; if ((key >= 0) && (key < 128)) val[i] = *(const u32x4*)(pa + i * stride); }
;             else if (i < 12) val[i] = *(const u32x4*)(pb + (i - 8) * stride); }
; __device__ __forceinline__ void compute_a(LAS unsigned char* lds, const UD& x, const bf16x8 (&qr)[4], int wid, int lane, u32x4 (&pw)[10], float& mx_o, float& l_o) {
;     ...
;         for (int r = 0; r < 16; ++r) { const float p = __builtin_amdgcn_exp2f(s[ht][r] - mx); s[ht][r] = p; lsum += p; }
;     lsum += __shfl_xor(lsum, 32);
; #pragma unroll
;     for (int g = 0; g < 10; ++g) {
;         const int ht = g >> 1, rb = (g & 1) * 8;
;         pw[g].x = pg8::cvt_pk_bf16(s[ht][rb + 0], s[ht][rb + 1]); pw[g].y = pg8::cvt_pk_bf16(s[ht][rb + 2], s[ht][rb + 3]); pw[g].z = pg8::cvt_pk_bf16(s[ht][rb + 4], s[ht][rb + 5]); pw[g].w = pg8::cvt_pk_bf16(s[ht][rb + 6], s[ht][rb + 7]);
;     }
	v_exp_f32_e32 v30, v17
	v_sub_f32_e32 v17, v31, v68
	v_add_f32_e32 v16, v27, v16
	v_exp_f32_e32 v31, v17
	v_sub_f32_e32 v0, v0, v68
	v_add_f32_e32 v16, v28, v16
	v_exp_f32_e32 v0, v0
	v_sub_f32_e32 v1, v1, v68
	v_add_f32_e32 v16, v29, v16
	v_exp_f32_e32 v1, v1
	v_sub_f32_e32 v2, v2, v68
	v_add_f32_e32 v16, v30, v16
	v_exp_f32_e32 v2, v2
	v_sub_f32_e32 v3, v3, v68
	v_add_f32_e32 v16, v31, v16
	v_exp_f32_e32 v3, v3
	v_sub_f32_e32 v4, v4, v68
	v_add_f32_e32 v16, v0, v16
	v_exp_f32_e32 v4, v4
	v_sub_f32_e32 v5, v5, v68
	v_add_f32_e32 v16, v1, v16
	v_exp_f32_e32 v5, v5
	v_sub_f32_e32 v6, v6, v68
	v_add_f32_e32 v16, v2, v16
	v_exp_f32_e32 v6, v6
	v_sub_f32_e32 v7, v7, v68
	v_add_f32_e32 v16, v3, v16
	v_exp_f32_e32 v7, v7
	v_sub_f32_e32 v8, v8, v68
	v_add_f32_e32 v16, v4, v16
	v_exp_f32_e32 v8, v8
	v_sub_f32_e32 v9, v9, v68
	v_add_f32_e32 v16, v5, v16
	v_exp_f32_e32 v9, v9
	v_sub_f32_e32 v10, v10, v68
	v_add_f32_e32 v16, v6, v16
	v_exp_f32_e32 v10, v10
	v_sub_f32_e32 v11, v11, v68
	v_add_f32_e32 v16, v7, v16
	v_exp_f32_e32 v11, v11
	v_sub_f32_e32 v12, v12, v68
	v_add_f32_e32 v16, v8, v16
	v_exp_f32_e32 v12, v12
	v_sub_f32_e32 v13, v13, v68
	v_add_f32_e32 v16, v9, v16
	v_exp_f32_e32 v13, v13
	v_sub_f32_e32 v14, v14, v68
	v_add_f32_e32 v16, v10, v16
	v_exp_f32_e32 v14, v14
	v_sub_f32_e32 v15, v15, v68
	v_add_f32_e32 v16, v11, v16
	v_exp_f32_e32 v15, v15
	v_sub_f32_e32 v17, v69, v68
	v_add_f32_e32 v16, v12, v16
	v_exp_f32_e32 v135, v17
	v_sub_f32_e32 v17, v70, v68
	v_add_f32_e32 v16, v13, v16
	v_exp_f32_e32 v70, v17
	v_sub_f32_e32 v17, v71, v68
	v_add_f32_e32 v16, v14, v16
	v_exp_f32_e32 v71, v17
	v_sub_f32_e32 v17, v72, v68
	v_add_f32_e32 v16, v15, v16
	v_exp_f32_e32 v72, v17
	v_sub_f32_e32 v17, v67, v68
	v_add_f32_e32 v16, v135, v16
	v_exp_f32_e32 v139, v17
	v_sub_f32_e32 v17, v66, v68
	v_add_f32_e32 v16, v70, v16
	v_exp_f32_e32 v149, v17
	v_sub_f32_e32 v17, v65, v68
	v_add_f32_e32 v16, v71, v16
	v_exp_f32_e32 v151, v17
	v_sub_f32_e32 v17, v64, v68
	v_add_f32_e32 v16, v72, v16
	v_exp_f32_e32 v196, v17
	v_sub_f32_e32 v17, v55, v68
	v_add_f32_e32 v16, v139, v16
	v_exp_f32_e32 v197, v17
	v_sub_f32_e32 v17, v54, v68
	v_add_f32_e32 v16, v149, v16
	v_exp_f32_e32 v198, v17
	v_sub_f32_e32 v17, v53, v68
	v_add_f32_e32 v16, v151, v16
	v_exp_f32_e32 v199, v17
	v_sub_f32_e32 v17, v52, v68
	v_add_f32_e32 v16, v196, v16
	v_exp_f32_e32 v229, v17
	v_sub_f32_e32 v17, v51, v68
	v_add_f32_e32 v16, v197, v16
	v_exp_f32_e32 v230, v17
	v_sub_f32_e32 v17, v50, v68
	v_add_f32_e32 v16, v198, v16
	v_exp_f32_e32 v231, v17
	v_sub_f32_e32 v17, v49, v68
	v_add_f32_e32 v16, v199, v16
	v_exp_f32_e32 v232, v17
	v_sub_f32_e32 v17, v48, v68
	v_add_f32_e32 v16, v229, v16
	v_exp_f32_e32 v233, v17
	v_add_f32_e32 v16, v230, v16
	v_add_f32_e32 v16, v231, v16
	v_add_f32_e32 v16, v232, v16
	v_add_f32_e32 v69, v233, v16
	v_cvt_pk_bf16_f32 v16, v56, v57
	v_cvt_pk_bf16_f32 v17, v58, v59
	v_cvt_pk_bf16_f32 v18, v60, v62
	v_cvt_pk_bf16_f32 v19, v63, v77
	v_cvt_pk_bf16_f32 v64, v78, v79
	v_cvt_pk_bf16_f32 v65, v82, v80
	v_cvt_pk_bf16_f32 v66, v76, v75
	v_cvt_pk_bf16_f32 v67, v74, v73
	v_cvt_pk_bf16_f32 v60, v32, v33
	v_cvt_pk_bf16_f32 v61, v34, v35
	v_cvt_pk_bf16_f32 v62, v36, v37
	v_cvt_pk_bf16_f32 v63, v38, v39
	v_cvt_pk_bf16_f32 v56, v40, v41
	v_cvt_pk_bf16_f32 v57, v42, v43
	v_cvt_pk_bf16_f32 v58, v44, v45
	v_cvt_pk_bf16_f32 v59, v46, v47
	v_cvt_pk_bf16_f32 v52, v83, v132
	v_cvt_pk_bf16_f32 v53, v133, v134
	v_cvt_pk_bf16_f32 v54, v20, v21
	v_cvt_pk_bf16_f32 v55, v22, v23
	v_cvt_pk_bf16_f32 v48, v24, v25
	v_cvt_pk_bf16_f32 v49, v26, v27
	v_cvt_pk_bf16_f32 v50, v28, v29
	v_cvt_pk_bf16_f32 v51, v30, v31
	v_cvt_pk_bf16_f32 v44, v0, v1
	v_cvt_pk_bf16_f32 v45, v2, v3
	v_cvt_pk_bf16_f32 v46, v4, v5
	v_cvt_pk_bf16_f32 v47, v6, v7
	v_cvt_pk_bf16_f32 v40, v8, v9
	v_cvt_pk_bf16_f32 v41, v10, v11
	v_cvt_pk_bf16_f32 v42, v12, v13
	v_cvt_pk_bf16_f32 v43, v14, v15
	v_cvt_pk_bf16_f32 v36, v135, v70
	ds_bpermute_b32 v70, v162, v69
	v_cvt_pk_bf16_f32 v37, v71, v72
	v_cvt_pk_bf16_f32 v38, v139, v149
	v_cvt_pk_bf16_f32 v39, v151, v196
	v_cvt_pk_bf16_f32 v32, v197, v198
	v_cvt_pk_bf16_f32 v33, v199, v229
	v_cvt_pk_bf16_f32 v34, v230, v231
	v_cvt_pk_bf16_f32 v35, v232, v233
	s_cbranch_vccnz .LBB0_799
	s_ashr_i32 s5, s14, 4
	s_mul_hi_i32 s4, s5, 0x2aaaaaab
	s_lshr_b32 s18, s4, 31
	s_ashr_i32 s4, s4, 1
	s_add_i32 s4, s4, s18
	s_mul_i32 s18, s4, 12
	s_sub_i32 s20, s5, s18
	s_ashr_i32 s5, s4, 31
	s_lshl_b64 s[18:19], s[4:5], 23
	v_lshl_add_u64 v[0:1], v[142:143], 0, s[18:19]
	v_mad_i64_i32 v[0:1], s[4:5], s4, v200, v[0:1]
	s_lshl_b32 s4, s20, 6
	s_ashr_i32 s5, s4, 31
	s_and_b32 s91, s14, 7
	v_lshl_add_u64 v[0:1], s[4:5], 1, v[0:1]
	v_mov_b32_e32 v139, v81
	v_lshl_add_u64 v[0:1], v[0:1], 0, v[138:139]
	s_bitcmp1_b32 s14, 3
	s_mov_b64 vcc, -1
	s_cbranch_scc0 .LBB0_773
	s_lshl_b32 s18, s91, 1
	v_or_b32_e32 v2, s18, v144
	v_mov_b32_e32 v88, v81
	v_mov_b32_e32 v89, v81
	v_mad_u64_u32 v[2:3], s[4:5], v2, s40, v[0:1]
	v_mov_b32_e32 v90, v81
	v_mov_b32_e32 v91, v81
	v_mov_b64_e32 v[84:85], v[88:89]
	v_readlane_b32 s20, v255, 22
	v_mad_i32_i24 v3, v145, s40, v3
	v_mov_b64_e32 v[86:87], v[90:91]
	v_readlane_b32 s21, v255, 23
	s_and_saveexec_b64 s[4:5], s[20:21]
	s_cbranch_execz .LBB0_758
	global_load_dwordx4 v[84:87], v[2:3], off

; __device__ __forceinline__ void compute_a(LAS unsigned char* lds, const UD& x, const bf16x8 (&qr)[4], int wid, int lane, u32x4 (&pw)[10], float& mx_o, float& l_o) {
;     ...
;     float mx = s[2][0];
; #pragma unroll
;     for (int ht = 0; ht < 5; ++ht)
; #pragma unroll
;         for (int r = 0; r < 16; ++r) mx = fmaxf(mx, s[ht][r]);
;     mx = fmaxf(mx, __shfl_xor(mx, 32));
;     float lsum = 0.f;
; #pragma unroll
;     for (int ht = 0; ht < 5; ++ht)
; #pragma unroll
;         for (int r = 0; r < 16; ++r) { const float p = __builtin_amdgcn_exp2f(s[ht][r] - mx); s[ht][r] = p; lsum += p; }
;     lsum += __shfl_xor(lsum, 32);
.LBB0_912:
	v_max3_f32 v56, v16, v83, v233
	v_max3_f32 v56, v56, v234, v235
	v_max3_f32 v56, v56, v236, v147
	v_max3_f32 v56, v56, v232, v145
	v_max3_f32 v56, v56, v143, v133
	v_max3_f32 v56, v56, v82, v80
	v_max3_f32 v56, v56, v76, v75
	v_max3_f32 v56, v56, v74, v73
	v_max3_f32 v56, v56, v32, v33
	v_max3_f32 v56, v56, v34, v35
	v_max3_f32 v56, v56, v36, v37
	v_max3_f32 v56, v56, v38, v39
	v_max3_f32 v56, v56, v40, v41
	v_max3_f32 v56, v56, v42, v43
	v_max3_f32 v56, v56, v44, v45
	v_max3_f32 v56, v56, v46, v47
	v_max3_f32 v56, v56, v16, v17
	v_max3_f32 v56, v56, v18, v19
	v_max3_f32 v56, v56, v20, v21
	v_max3_f32 v56, v56, v22, v23
	v_max3_f32 v56, v56, v24, v25
	v_max3_f32 v56, v56, v26, v27
	v_max3_f32 v56, v56, v28, v29
	v_max3_f32 v56, v56, v30, v31
	v_max3_f32 v56, v56, v0, v1
	v_max3_f32 v56, v56, v2, v3
	v_max3_f32 v56, v56, v4, v5
	v_max3_f32 v56, v56, v6, v7
	v_max3_f32 v56, v56, v8, v9
	v_max3_f32 v56, v56, v10, v11
	v_max3_f32 v56, v56, v12, v13
	v_max3_f32 v56, v56, v14, v15
	v_max3_f32 v56, v56, v69, v70
	v_max3_f32 v56, v56, v71, v72
	v_max3_f32 v56, v56, v66, v67
	v_max3_f32 v56, v56, v65, v64
	v_max3_f32 v56, v56, v55, v54
	v_max3_f32 v56, v56, v53, v52
	v_max3_f32 v56, v56, v51, v50
	v_max3_f32 v56, v56, v49, v48
	v_mov_b32_e32 v57, v56
	v_mov_b32_e32 v58, v56
	s_nop 1
	v_permlane32_swap_b32_e32 v57, v58
	s_add_i32 s68, s18, 32
	v_readlane_b32 s19, v253, 57
	s_cmp_ge_i32 s18, s19
	s_cselect_b64 s[52:53], -1, 0
	s_waitcnt lgkmcnt(0)
	s_nop 0
	v_max_f32_e32 v68, v57, v58
	v_sub_f32_e32 v56, v83, v68
	v_sub_f32_e32 v57, v233, v68
	v_exp_f32_e32 v56, v56
	v_sub_f32_e32 v58, v234, v68
	v_exp_f32_e32 v57, v57
	v_sub_f32_e32 v59, v235, v68
	v_exp_f32_e32 v58, v58
	v_sub_f32_e32 v60, v236, v68
	v_exp_f32_e32 v59, v59
	v_add_f32_e32 v61, 0, v56
	v_exp_f32_e32 v60, v60
	v_sub_f32_e32 v62, v147, v68
	v_add_f32_e32 v61, v57, v61
	v_exp_f32_e32 v62, v62
	v_sub_f32_e32 v63, v232, v68
	v_add_f32_e32 v61, v58, v61
	v_exp_f32_e32 v63, v63
	v_sub_f32_e32 v77, v145, v68
	v_add_f32_e32 v61, v59, v61
	v_exp_f32_e32 v77, v77
	v_sub_f32_e32 v78, v143, v68
	v_add_f32_e32 v61, v60, v61
	v_exp_f32_e32 v78, v78
	v_sub_f32_e32 v79, v133, v68
	v_add_f32_e32 v61, v62, v61
	v_exp_f32_e32 v79, v79
	v_sub_f32_e32 v82, v82, v68
	v_add_f32_e32 v61, v63, v61
	v_exp_f32_e32 v82, v82
	v_sub_f32_e32 v80, v80, v68
	v_add_f32_e32 v61, v77, v61
	v_exp_f32_e32 v80, v80
	v_sub_f32_e32 v76, v76, v68
	v_add_f32_e32 v61, v78, v61
	v_exp_f32_e32 v76, v76
	v_sub_f32_e32 v75, v75, v68
	v_add_f32_e32 v61, v79, v61
	v_exp_f32_e32 v75, v75
	v_sub_f32_e32 v74, v74, v68
	v_add_f32_e32 v61, v82, v61
	v_exp_f32_e32 v74, v74
	v_sub_f32_e32 v73, v73, v68
	v_add_f32_e32 v61, v80, v61
	v_exp_f32_e32 v73, v73
	v_sub_f32_e32 v32, v32, v68
	v_add_f32_e32 v61, v76, v61
	v_exp_f32_e32 v32, v32
	v_sub_f32_e32 v33, v33, v68
	v_add_f32_e32 v61, v75, v61
	v_exp_f32_e32 v33, v33
	v_sub_f32_e32 v34, v34, v68
	v_add_f32_e32 v61, v74, v61
	v_exp_f32_e32 v34, v34
	v_sub_f32_e32 v35, v35, v68
	v_add_f32_e32 v61, v73, v61
	v_exp_f32_e32 v35, v35
	v_sub_f32_e32 v36, v36, v68
	v_add_f32_e32 v61, v32, v61
	v_exp_f32_e32 v36, v36
	v_sub_f32_e32 v37, v37, v68
	v_add_f32_e32 v61, v33, v61
	v_exp_f32_e32 v37, v37
	v_sub_f32_e32 v38, v38, v68
	v_add_f32_e32 v61, v34, v61
	v_exp_f32_e32 v38, v38
	v_sub_f32_e32 v39, v39, v68
	v_add_f32_e32 v61, v35, v61
	v_exp_f32_e32 v39, v39
	v_sub_f32_e32 v40, v40, v68
	v_add_f32_e32 v61, v36, v61
	v_exp_f32_e32 v40, v40
	v_sub_f32_e32 v41, v41, v68
	v_add_f32_e32 v61, v37, v61
	v_exp_f32_e32 v41, v41
	v_sub_f32_e32 v42, v42, v68
	v_add_f32_e32 v61, v38, v61
	v_exp_f32_e32 v42, v42
	v_sub_f32_e32 v43, v43, v68
	v_add_f32_e32 v61, v39, v61
	v_exp_f32_e32 v43, v43
	v_sub_f32_e32 v44, v44, v68
	v_add_f32_e32 v61, v40, v61
	v_exp_f32_e32 v44, v44
	v_sub_f32_e32 v45, v45, v68
	v_add_f32_e32 v61, v41, v61
	v_exp_f32_e32 v45, v45
	v_sub_f32_e32 v46, v46, v68
	v_add_f32_e32 v61, v42, v61
	v_exp_f32_e32 v46, v46
	v_sub_f32_e32 v47, v47, v68
	v_add_f32_e32 v61, v43, v61
	v_exp_f32_e32 v47, v47
	v_sub_f32_e32 v16, v16, v68
	v_add_f32_e32 v61, v44, v61
	v_exp_f32_e32 v83, v16
	v_sub_f32_e32 v16, v17, v68
	v_add_f32_e32 v61, v45, v61
	v_exp_f32_e32 v133, v16
	v_sub_f32_e32 v16, v18, v68
	v_add_f32_e32 v61, v46, v61
	v_exp_f32_e32 v143, v16
	v_sub_f32_e32 v16, v19, v68
	v_add_f32_e32 v61, v47, v61
	v_exp_f32_e32 v145, v16
	v_sub_f32_e32 v17, v20, v68
	v_add_f32_e32 v16, v83, v61
	v_exp_f32_e32 v20, v17
	v_sub_f32_e32 v17, v21, v68
	v_add_f32_e32 v16, v133, v16
	v_exp_f32_e32 v21, v17
	v_sub_f32_e32 v17, v22, v68
	v_add_f32_e32 v16, v143, v16
	v_exp_f32_e32 v22, v17
	v_sub_f32_e32 v17, v23, v68
	v_add_f32_e32 v16, v145, v16
	v_exp_f32_e32 v23, v17
	v_sub_f32_e32 v17, v24, v68
	v_add_f32_e32 v16, v20, v16
	v_exp_f32_e32 v24, v17
	v_sub_f32_e32 v17, v25, v68
	v_add_f32_e32 v16, v21, v16
	v_exp_f32_e32 v25, v17
	v_sub_f32_e32 v17, v26, v68
	v_add_f32_e32 v16, v22, v16
	v_exp_f32_e32 v26, v17
	v_sub_f32_e32 v17, v27, v68
	v_add_f32_e32 v16, v23, v16
	v_exp_f32_e32 v27, v17
	v_sub_f32_e32 v17, v28, v68
	v_add_f32_e32 v16, v24, v16
	v_exp_f32_e32 v28, v17
	v_sub_f32_e32 v17, v29, v68
	v_add_f32_e32 v16, v25, v16
	v_exp_f32_e32 v29, v17
; __device__ __forceinline__ unsigned cvt_pk_bf16(float lo, float hi) { unsigned r; asm volatile("v_cvt_pk_bf16_f32 %0, %1, %2" : "=v"(r) : "v"(lo), "v"(hi)); return r; }
; __device__ __forceinline__ void load_kv(u32x4 (&val)[14], const UD& x, const unsigned char* ws, int tid) {
;     const int br = x.br, u = x.u, sub = tid & 15, s0 = tid >> 4;
;     const bf16_t* base = (const bf16_t*)(ws + ((sub < 8) ? off_k(x.b) : off_v(x.b))) + (size_t)x.b * SEQ * AW + x.h * HD + (sub & 7) * 8;
;     if (br < 2) {
;         const int d = (br == 0) ? 1 : 4, L = SEQ / d, T0 = (br == 0) ? 256 * u : 256 * (u & 1), cls = (br == 0) ? 0 : (u >> 1);
;         const int k0 = T0 - 64 + s0;
;         const bf16_t* p0 = base + ((long)k0 * d + cls) * AW; const long stride = (long)32 * d * AW;
; #pragma unroll
;         for (int i = 0; i < 14; ++i) { const int key = k0 + 32 * i; val[i] = (u32x4){0u, 0u, 0u, 0u};
;             if ((i < 12) && (key >= 0) && (key < L)) val[i] = *(const u32x4*)(p0 + i * stride); }
; __device__ __forceinline__ void compute_a(LAS unsigned char* lds, const UD& x, const bf16x8 (&qr)[4], int wid, int lane, u32x4 (&pw)[10], float& mx_o, float& l_o) {
;     ...
;         for (int r = 0; r < 16; ++r) { const float p = __builtin_amdgcn_exp2f(s[ht][r] - mx); s[ht][r] = p; lsum += p; }
;     lsum += __shfl_xor(lsum, 32);
; #pragma unroll
;     for (int g = 0; g < 10; ++g) {
;         const int ht = g >> 1, rb = (g & 1) * 8;
;         pw[g].x = pg8::cvt_pk_bf16(s[ht][rb + 0], s[ht][rb + 1]); pw[g].y = pg8::cvt_pk_bf16(s[ht][rb + 2], s[ht][rb + 3]); pw[g].z = pg8::cvt_pk_bf16(s[ht][rb + 4], s[ht][rb + 5]); pw[g].w = pg8::cvt_pk_bf16(s[ht][rb + 6], s[ht][rb + 7]);
;     }
	v_sub_f32_e32 v17, v30, v68
	v_add_f32_e32 v16, v26, v16
	v_exp_f32_e32 v30, v17
	v_sub_f32_e32 v17, v31, v68
	v_add_f32_e32 v16, v27, v16
	v_exp_f32_e32 v31, v17
	v_sub_f32_e32 v0, v0, v68
	v_add_f32_e32 v16, v28, v16
	v_exp_f32_e32 v0, v0
	v_sub_f32_e32 v1, v1, v68
	v_add_f32_e32 v16, v29, v16
	v_exp_f32_e32 v1, v1
	v_sub_f32_e32 v2, v2, v68
	v_add_f32_e32 v16, v30, v16
	v_exp_f32_e32 v2, v2
	v_sub_f32_e32 v3, v3, v68
	v_add_f32_e32 v16, v31, v16
	v_exp_f32_e32 v3, v3
	v_sub_f32_e32 v4, v4, v68
	v_add_f32_e32 v16, v0, v16
	v_exp_f32_e32 v4, v4
	v_sub_f32_e32 v5, v5, v68
	v_add_f32_e32 v16, v1, v16
	v_exp_f32_e32 v5, v5
	v_sub_f32_e32 v6, v6, v68
	v_add_f32_e32 v16, v2, v16
	v_exp_f32_e32 v6, v6
	v_sub_f32_e32 v7, v7, v68
	v_add_f32_e32 v16, v3, v16
	v_exp_f32_e32 v7, v7
	v_sub_f32_e32 v8, v8, v68
	v_add_f32_e32 v16, v4, v16
	v_exp_f32_e32 v8, v8
	v_sub_f32_e32 v9, v9, v68
	v_add_f32_e32 v16, v5, v16
	v_exp_f32_e32 v9, v9
	v_sub_f32_e32 v10, v10, v68
	v_add_f32_e32 v16, v6, v16
	v_exp_f32_e32 v10, v10
	v_sub_f32_e32 v11, v11, v68
	v_add_f32_e32 v16, v7, v16
	v_exp_f32_e32 v11, v11
	v_sub_f32_e32 v12, v12, v68
	v_add_f32_e32 v16, v8, v16
	v_exp_f32_e32 v12, v12
	v_sub_f32_e32 v13, v13, v68
	v_add_f32_e32 v16, v9, v16
	v_exp_f32_e32 v13, v13
	v_sub_f32_e32 v14, v14, v68
	v_add_f32_e32 v16, v10, v16
	v_exp_f32_e32 v14, v14
	v_sub_f32_e32 v15, v15, v68
	v_add_f32_e32 v16, v11, v16
	v_exp_f32_e32 v15, v15
	v_sub_f32_e32 v17, v69, v68
	v_add_f32_e32 v16, v12, v16
	v_exp_f32_e32 v147, v17
	v_sub_f32_e32 v17, v70, v68
	v_add_f32_e32 v16, v13, v16
	v_exp_f32_e32 v70, v17
	v_sub_f32_e32 v17, v71, v68
	v_add_f32_e32 v16, v14, v16
	v_exp_f32_e32 v71, v17
	v_sub_f32_e32 v17, v72, v68
	v_add_f32_e32 v16, v15, v16
	v_exp_f32_e32 v72, v17
	v_sub_f32_e32 v17, v66, v68
	v_add_f32_e32 v16, v147, v16
	v_exp_f32_e32 v196, v17
	v_sub_f32_e32 v17, v67, v68
	v_add_f32_e32 v16, v70, v16
	v_exp_f32_e32 v197, v17
	v_sub_f32_e32 v17, v65, v68
	v_add_f32_e32 v16, v71, v16
	v_exp_f32_e32 v198, v17
	v_sub_f32_e32 v17, v64, v68
	v_add_f32_e32 v16, v72, v16
	v_exp_f32_e32 v199, v17
	v_sub_f32_e32 v17, v55, v68
	v_add_f32_e32 v16, v196, v16
	v_exp_f32_e32 v232, v17
	v_sub_f32_e32 v17, v54, v68
	v_add_f32_e32 v16, v197, v16
	v_exp_f32_e32 v233, v17
	v_sub_f32_e32 v17, v53, v68
	v_add_f32_e32 v16, v198, v16
	v_exp_f32_e32 v234, v17
	v_sub_f32_e32 v17, v52, v68
	v_add_f32_e32 v16, v199, v16
	v_exp_f32_e32 v235, v17
	v_sub_f32_e32 v17, v51, v68
	v_add_f32_e32 v16, v232, v16
	v_exp_f32_e32 v236, v17
	v_sub_f32_e32 v17, v50, v68
	v_add_f32_e32 v16, v233, v16
	v_exp_f32_e32 v237, v17
	v_sub_f32_e32 v17, v49, v68
	v_add_f32_e32 v16, v234, v16
	v_exp_f32_e32 v242, v17
	v_sub_f32_e32 v17, v48, v68
	v_add_f32_e32 v16, v235, v16
	v_exp_f32_e32 v243, v17
	v_add_f32_e32 v16, v236, v16
	v_add_f32_e32 v16, v237, v16
	v_add_f32_e32 v16, v242, v16
	v_add_f32_e32 v69, v243, v16
	v_cvt_pk_bf16_f32 v16, v56, v57
	v_cvt_pk_bf16_f32 v17, v58, v59
	v_cvt_pk_bf16_f32 v18, v60, v62
	v_cvt_pk_bf16_f32 v19, v63, v77
	v_cvt_pk_bf16_f32 v64, v78, v79
	v_cvt_pk_bf16_f32 v65, v82, v80
	v_cvt_pk_bf16_f32 v66, v76, v75
	v_cvt_pk_bf16_f32 v67, v74, v73
	v_cvt_pk_bf16_f32 v60, v32, v33
	v_cvt_pk_bf16_f32 v61, v34, v35
	v_cvt_pk_bf16_f32 v62, v36, v37
	v_cvt_pk_bf16_f32 v63, v38, v39
	v_cvt_pk_bf16_f32 v56, v40, v41
	v_cvt_pk_bf16_f32 v57, v42, v43
	v_cvt_pk_bf16_f32 v58, v44, v45
	v_cvt_pk_bf16_f32 v59, v46, v47
	v_cvt_pk_bf16_f32 v52, v83, v133
	v_cvt_pk_bf16_f32 v53, v143, v145
	v_cvt_pk_bf16_f32 v54, v20, v21
	v_cvt_pk_bf16_f32 v55, v22, v23
	v_cvt_pk_bf16_f32 v48, v24, v25
	v_cvt_pk_bf16_f32 v49, v26, v27
	v_cvt_pk_bf16_f32 v50, v28, v29
	v_cvt_pk_bf16_f32 v51, v30, v31
	v_cvt_pk_bf16_f32 v44, v0, v1
	v_cvt_pk_bf16_f32 v45, v2, v3
	v_cvt_pk_bf16_f32 v46, v4, v5
	v_cvt_pk_bf16_f32 v47, v6, v7
	v_cvt_pk_bf16_f32 v40, v8, v9
	v_cvt_pk_bf16_f32 v41, v10, v11
	v_cvt_pk_bf16_f32 v42, v12, v13
	v_cvt_pk_bf16_f32 v43, v14, v15
	v_cvt_pk_bf16_f32 v36, v147, v70
	ds_bpermute_b32 v70, v151, v69
	s_and_b64 vcc, exec, s[52:53]
	v_cvt_pk_bf16_f32 v37, v71, v72
	v_cvt_pk_bf16_f32 v38, v196, v197
	v_cvt_pk_bf16_f32 v39, v198, v199
	v_cvt_pk_bf16_f32 v32, v232, v233
	v_cvt_pk_bf16_f32 v33, v234, v235
	v_cvt_pk_bf16_f32 v34, v236, v237
	v_cvt_pk_bf16_f32 v35, v242, v243
	s_cbranch_vccnz .LBB0_938
	s_ashr_i32 s19, s68, 3
	s_mul_hi_i32 s18, s19, 0x2aaaaaab
	s_lshr_b32 s23, s18, 31
	s_ashr_i32 s18, s18, 1
	s_add_i32 s18, s18, s23
	s_mul_i32 s23, s18, 12
	s_sub_i32 s23, s19, s23
	s_ashr_i32 s19, s18, 31
	s_lshl_b64 s[24:25], s[18:19], 23
	v_lshl_add_u64 v[0:1], v[134:135], 0, s[24:25]
	v_mad_i64_i32 v[0:1], s[18:19], s18, v200, v[0:1]
	s_lshl_b32 s18, s23, 6
	s_ashr_i32 s19, s18, 31
	v_lshl_add_u64 v[0:1], s[18:19], 1, v[0:1]
	v_mov_b32_e32 v133, v81
	v_mov_b32_e32 v88, v81
	v_mov_b32_e32 v89, v81
	v_lshl_add_u64 v[0:1], v[0:1], 0, v[132:133]
	v_add_u32_e32 v2, s21, v149
	v_mov_b32_e32 v90, v81
	v_mov_b32_e32 v91, v81
	v_mov_b64_e32 v[84:85], v[88:89]
	v_mad_i64_i32 v[0:1], s[18:19], v2, s40, v[0:1]
	v_cmp_gt_u32_e32 vcc, s44, v2
	v_mov_b64_e32 v[86:87], v[90:91]
	s_and_saveexec_b64 s[18:19], vcc
	s_cbranch_execz .LBB0_915
	global_load_dwordx4 v[84:87], v[0:1], off

; __device__ __forceinline__ void compute_a(LAS unsigned char* lds, const UD& x, const bf16x8 (&qr)[4], int wid, int lane, u32x4 (&pw)[10], float& mx_o, float& l_o) {
;     ...
;     float mx = s[2][0];
; #pragma unroll
;     for (int ht = 0; ht < 5; ++ht)
; #pragma unroll
;         for (int r = 0; r < 16; ++r) mx = fmaxf(mx, s[ht][r]);
;     mx = fmaxf(mx, __shfl_xor(mx, 32));
;     float lsum = 0.f;
; #pragma unroll
;     for (int ht = 0; ht < 5; ++ht)
; #pragma unroll
;         for (int r = 0; r < 16; ++r) { const float p = __builtin_amdgcn_exp2f(s[ht][r] - mx); s[ht][r] = p; lsum += p; }
;     lsum += __shfl_xor(lsum, 32);
.LBB0_1015:
	v_max3_f32 v56, v16, v83, v233
	v_max3_f32 v56, v56, v234, v235
	v_max3_f32 v56, v56, v236, v147
	v_max3_f32 v56, v56, v232, v145
	v_max3_f32 v56, v56, v143, v133
	v_max3_f32 v56, v56, v82, v80
	v_max3_f32 v56, v56, v76, v75
	v_max3_f32 v56, v56, v74, v73
	v_max3_f32 v56, v56, v32, v33
	v_max3_f32 v56, v56, v34, v35
	v_max3_f32 v56, v56, v36, v37
	v_max3_f32 v56, v56, v38, v39
	v_max3_f32 v56, v56, v40, v41
	v_max3_f32 v56, v56, v42, v43
	v_max3_f32 v56, v56, v44, v45
	v_max3_f32 v56, v56, v46, v47
	v_max3_f32 v56, v56, v16, v17
	v_max3_f32 v56, v56, v18, v19
	v_max3_f32 v56, v56, v20, v21
	v_max3_f32 v56, v56, v22, v23
	v_max3_f32 v56, v56, v24, v25
	v_max3_f32 v56, v56, v26, v27
	v_max3_f32 v56, v56, v28, v29
	v_max3_f32 v56, v56, v30, v31
	v_max3_f32 v56, v56, v0, v1
	v_max3_f32 v56, v56, v2, v3
	v_max3_f32 v56, v56, v4, v5
	v_max3_f32 v56, v56, v6, v7
	v_max3_f32 v56, v56, v8, v9
	v_max3_f32 v56, v56, v10, v11
	v_max3_f32 v56, v56, v12, v13
	v_max3_f32 v56, v56, v14, v15
	v_max3_f32 v56, v56, v69, v70
	v_max3_f32 v56, v56, v71, v72
	v_max3_f32 v56, v56, v66, v67
	v_max3_f32 v56, v56, v65, v64
	v_max3_f32 v56, v56, v55, v54
	v_max3_f32 v56, v56, v53, v52
	v_max3_f32 v56, v56, v51, v50
	v_max3_f32 v56, v56, v49, v48
	v_mov_b32_e32 v57, v56
	v_mov_b32_e32 v58, v56
	s_nop 1
	v_permlane32_swap_b32_e32 v57, v58
	s_add_i32 s68, s68, s72
	s_cmpk_gt_i32 s68, 0x2ff
	s_cselect_b64 s[52:53], -1, 0
	s_and_b64 vcc, exec, s[52:53]
	s_waitcnt lgkmcnt(0)
	s_nop 0
	v_max_f32_e32 v68, v57, v58
	v_sub_f32_e32 v56, v83, v68
	v_sub_f32_e32 v57, v233, v68
	v_exp_f32_e32 v56, v56
	v_sub_f32_e32 v58, v234, v68
	v_exp_f32_e32 v57, v57
	v_sub_f32_e32 v59, v235, v68
	v_exp_f32_e32 v58, v58
	v_sub_f32_e32 v60, v236, v68
	v_exp_f32_e32 v59, v59
	v_add_f32_e32 v61, 0, v56
	v_exp_f32_e32 v60, v60
	v_sub_f32_e32 v62, v147, v68
	v_add_f32_e32 v61, v57, v61
	v_exp_f32_e32 v62, v62
	v_sub_f32_e32 v63, v232, v68
	v_add_f32_e32 v61, v58, v61
	v_exp_f32_e32 v63, v63
	v_sub_f32_e32 v77, v145, v68
	v_add_f32_e32 v61, v59, v61
	v_exp_f32_e32 v77, v77
	v_sub_f32_e32 v78, v143, v68
	v_add_f32_e32 v61, v60, v61
	v_exp_f32_e32 v78, v78
	v_sub_f32_e32 v79, v133, v68
	v_add_f32_e32 v61, v62, v61
	v_exp_f32_e32 v79, v79
	v_sub_f32_e32 v82, v82, v68
	v_add_f32_e32 v61, v63, v61
	v_exp_f32_e32 v82, v82
	v_sub_f32_e32 v80, v80, v68
	v_add_f32_e32 v61, v77, v61
	v_exp_f32_e32 v80, v80
	v_sub_f32_e32 v76, v76, v68
	v_add_f32_e32 v61, v78, v61
	v_exp_f32_e32 v76, v76
	v_sub_f32_e32 v75, v75, v68
	v_add_f32_e32 v61, v79, v61
	v_exp_f32_e32 v75, v75
	v_sub_f32_e32 v74, v74, v68
	v_add_f32_e32 v61, v82, v61
	v_exp_f32_e32 v74, v74
	v_sub_f32_e32 v73, v73, v68
	v_add_f32_e32 v61, v80, v61
	v_exp_f32_e32 v73, v73
	v_sub_f32_e32 v32, v32, v68
	v_add_f32_e32 v61, v76, v61
	v_exp_f32_e32 v32, v32
	v_sub_f32_e32 v33, v33, v68
	v_add_f32_e32 v61, v75, v61
	v_exp_f32_e32 v33, v33
	v_sub_f32_e32 v34, v34, v68
	v_add_f32_e32 v61, v74, v61
	v_exp_f32_e32 v34, v34
	v_sub_f32_e32 v35, v35, v68
	v_add_f32_e32 v61, v73, v61
	v_exp_f32_e32 v35, v35
	v_sub_f32_e32 v36, v36, v68
	v_add_f32_e32 v61, v32, v61
	v_exp_f32_e32 v36, v36
	v_sub_f32_e32 v37, v37, v68
	v_add_f32_e32 v61, v33, v61
	v_exp_f32_e32 v37, v37
	v_sub_f32_e32 v38, v38, v68
	v_add_f32_e32 v61, v34, v61
	v_exp_f32_e32 v38, v38
	v_sub_f32_e32 v39, v39, v68
	v_add_f32_e32 v61, v35, v61
	v_exp_f32_e32 v39, v39
	v_sub_f32_e32 v40, v40, v68
	v_add_f32_e32 v61, v36, v61
	v_exp_f32_e32 v40, v40
	v_sub_f32_e32 v41, v41, v68
	v_add_f32_e32 v61, v37, v61
	v_exp_f32_e32 v41, v41
	v_sub_f32_e32 v42, v42, v68
	v_add_f32_e32 v61, v38, v61
	v_exp_f32_e32 v42, v42
	v_sub_f32_e32 v43, v43, v68
	v_add_f32_e32 v61, v39, v61
	v_exp_f32_e32 v43, v43
	v_sub_f32_e32 v44, v44, v68
	v_add_f32_e32 v61, v40, v61
	v_exp_f32_e32 v44, v44
	v_sub_f32_e32 v45, v45, v68
	v_add_f32_e32 v61, v41, v61
	v_exp_f32_e32 v45, v45
	v_sub_f32_e32 v46, v46, v68
	v_add_f32_e32 v61, v42, v61
	v_exp_f32_e32 v46, v46
	v_sub_f32_e32 v47, v47, v68
	v_add_f32_e32 v61, v43, v61
	v_exp_f32_e32 v47, v47
	v_sub_f32_e32 v16, v16, v68
	v_add_f32_e32 v61, v44, v61
	v_exp_f32_e32 v83, v16
	v_sub_f32_e32 v16, v17, v68
	v_add_f32_e32 v61, v45, v61
	v_exp_f32_e32 v133, v16
	v_sub_f32_e32 v16, v18, v68
	v_add_f32_e32 v61, v46, v61
	v_exp_f32_e32 v143, v16
	v_sub_f32_e32 v16, v19, v68
	v_add_f32_e32 v61, v47, v61
	v_exp_f32_e32 v145, v16
	v_sub_f32_e32 v17, v20, v68
	v_add_f32_e32 v16, v83, v61
	v_exp_f32_e32 v20, v17
	v_sub_f32_e32 v17, v21, v68
	v_add_f32_e32 v16, v133, v16
	v_exp_f32_e32 v21, v17
	v_sub_f32_e32 v17, v22, v68
	v_add_f32_e32 v16, v143, v16
	v_exp_f32_e32 v22, v17
	v_sub_f32_e32 v17, v23, v68
	v_add_f32_e32 v16, v145, v16
	v_exp_f32_e32 v23, v17
	v_sub_f32_e32 v17, v24, v68
	v_add_f32_e32 v16, v20, v16
	v_exp_f32_e32 v24, v17
	v_sub_f32_e32 v17, v25, v68
	v_add_f32_e32 v16, v21, v16
	v_exp_f32_e32 v25, v17
	v_sub_f32_e32 v17, v26, v68
	v_add_f32_e32 v16, v22, v16
	v_exp_f32_e32 v26, v17
	v_sub_f32_e32 v17, v27, v68
	v_add_f32_e32 v16, v23, v16
	v_exp_f32_e32 v27, v17
	v_sub_f32_e32 v17, v28, v68
	v_add_f32_e32 v16, v24, v16
	v_exp_f32_e32 v28, v17
	v_sub_f32_e32 v17, v29, v68
	v_add_f32_e32 v16, v25, v16
	v_exp_f32_e32 v29, v17
; __device__ __forceinline__ unsigned cvt_pk_bf16(float lo, float hi) { unsigned r; asm volatile("v_cvt_pk_bf16_f32 %0, %1, %2" : "=v"(r) : "v"(lo), "v"(hi)); return r; }
; __device__ __forceinline__ void load_kv(u32x4 (&val)[14], const UD& x, const unsigned char* ws, int tid) {
;     const int br = x.br, u = x.u, sub = tid & 15, s0 = tid >> 4;
;     const bf16_t* base = (const bf16_t*)(ws + ((sub < 8) ? off_k(x.b) : off_v(x.b))) + (size_t)x.b * SEQ * AW + x.h * HD + (sub & 7) * 8;
;     if (br < 2) {
;         const int d = (br == 0) ? 1 : 4, L = SEQ / d, T0 = (br == 0) ? 256 * u : 256 * (u & 1), cls = (br == 0) ? 0 : (u >> 1);
;         const int k0 = T0 - 64 + s0;
;         const bf16_t* p0 = base + ((long)k0 * d + cls) * AW; const long stride = (long)32 * d * AW;
; #pragma unroll
;         for (int i = 0; i < 14; ++i) { const int key = k0 + 32 * i; val[i] = (u32x4){0u, 0u, 0u, 0u};
;             if ((i < 12) && (key >= 0) && (key < L)) val[i] = *(const u32x4*)(p0 + i * stride); }
; __device__ __forceinline__ void compute_a(LAS unsigned char* lds, const UD& x, const bf16x8 (&qr)[4], int wid, int lane, u32x4 (&pw)[10], float& mx_o, float& l_o) {
;     ...
;     float lsum = 0.f;
; #pragma unroll
;     for (int ht = 0; ht < 5; ++ht)
; #pragma unroll
;         for (int r = 0; r < 16; ++r) { const float p = __builtin_amdgcn_exp2f(s[ht][r] - mx); s[ht][r] = p; lsum += p; }
;     lsum += __shfl_xor(lsum, 32);
; #pragma unroll
;     for (int g = 0; g < 10; ++g) {
;         const int ht = g >> 1, rb = (g & 1) * 8;
;         pw[g].x = pg8::cvt_pk_bf16(s[ht][rb + 0], s[ht][rb + 1]); pw[g].y = pg8::cvt_pk_bf16(s[ht][rb + 2], s[ht][rb + 3]); pw[g].z = pg8::cvt_pk_bf16(s[ht][rb + 4], s[ht][rb + 5]); pw[g].w = pg8::cvt_pk_bf16(s[ht][rb + 6], s[ht][rb + 7]);
;     }
	v_sub_f32_e32 v17, v30, v68
	v_add_f32_e32 v16, v26, v16
	v_exp_f32_e32 v30, v17
	v_sub_f32_e32 v17, v31, v68
	v_add_f32_e32 v16, v27, v16
	v_exp_f32_e32 v31, v17
	v_sub_f32_e32 v0, v0, v68
	v_add_f32_e32 v16, v28, v16
	v_exp_f32_e32 v0, v0
	v_sub_f32_e32 v1, v1, v68
	v_add_f32_e32 v16, v29, v16
	v_exp_f32_e32 v1, v1
	v_sub_f32_e32 v2, v2, v68
	v_add_f32_e32 v16, v30, v16
	v_exp_f32_e32 v2, v2
	v_sub_f32_e32 v3, v3, v68
	v_add_f32_e32 v16, v31, v16
	v_exp_f32_e32 v3, v3
	v_sub_f32_e32 v4, v4, v68
	v_add_f32_e32 v16, v0, v16
	v_exp_f32_e32 v4, v4
	v_sub_f32_e32 v5, v5, v68
	v_add_f32_e32 v16, v1, v16
	v_exp_f32_e32 v5, v5
	v_sub_f32_e32 v6, v6, v68
	v_add_f32_e32 v16, v2, v16
	v_exp_f32_e32 v6, v6
	v_sub_f32_e32 v7, v7, v68
	v_add_f32_e32 v16, v3, v16
	v_exp_f32_e32 v7, v7
	v_sub_f32_e32 v8, v8, v68
	v_add_f32_e32 v16, v4, v16
	v_exp_f32_e32 v8, v8
	v_sub_f32_e32 v9, v9, v68
	v_add_f32_e32 v16, v5, v16
	v_exp_f32_e32 v9, v9
	v_sub_f32_e32 v10, v10, v68
	v_add_f32_e32 v16, v6, v16
	v_exp_f32_e32 v10, v10
	v_sub_f32_e32 v11, v11, v68
	v_add_f32_e32 v16, v7, v16
	v_exp_f32_e32 v11, v11
	v_sub_f32_e32 v12, v12, v68
	v_add_f32_e32 v16, v8, v16
	v_exp_f32_e32 v12, v12
	v_sub_f32_e32 v13, v13, v68
	v_add_f32_e32 v16, v9, v16
	v_exp_f32_e32 v13, v13
	v_sub_f32_e32 v14, v14, v68
	v_add_f32_e32 v16, v10, v16
	v_exp_f32_e32 v14, v14
	v_sub_f32_e32 v15, v15, v68
	v_add_f32_e32 v16, v11, v16
	v_exp_f32_e32 v15, v15
	v_sub_f32_e32 v17, v69, v68
	v_add_f32_e32 v16, v12, v16
	v_exp_f32_e32 v147, v17
	v_sub_f32_e32 v17, v70, v68
	v_add_f32_e32 v16, v13, v16
	v_exp_f32_e32 v70, v17
	v_sub_f32_e32 v17, v71, v68
	v_add_f32_e32 v16, v14, v16
	v_exp_f32_e32 v71, v17
	v_sub_f32_e32 v17, v72, v68
	v_add_f32_e32 v16, v15, v16
	v_exp_f32_e32 v72, v17
	v_sub_f32_e32 v17, v66, v68
	v_add_f32_e32 v16, v147, v16
	v_exp_f32_e32 v196, v17
	v_sub_f32_e32 v17, v67, v68
	v_add_f32_e32 v16, v70, v16
	v_exp_f32_e32 v197, v17
	v_sub_f32_e32 v17, v65, v68
	v_add_f32_e32 v16, v71, v16
	v_exp_f32_e32 v198, v17
	v_sub_f32_e32 v17, v64, v68
	v_add_f32_e32 v16, v72, v16
	v_exp_f32_e32 v199, v17
	v_sub_f32_e32 v17, v55, v68
	v_add_f32_e32 v16, v196, v16
	v_exp_f32_e32 v232, v17
	v_sub_f32_e32 v17, v54, v68
	v_add_f32_e32 v16, v197, v16
	v_exp_f32_e32 v233, v17
	v_sub_f32_e32 v17, v53, v68
	v_add_f32_e32 v16, v198, v16
	v_exp_f32_e32 v234, v17
	v_sub_f32_e32 v17, v52, v68
	v_add_f32_e32 v16, v199, v16
	v_exp_f32_e32 v235, v17
	v_sub_f32_e32 v17, v51, v68
	v_add_f32_e32 v16, v232, v16
	v_exp_f32_e32 v236, v17
	v_sub_f32_e32 v17, v50, v68
	v_add_f32_e32 v16, v233, v16
	v_exp_f32_e32 v237, v17
	v_sub_f32_e32 v17, v49, v68
	v_add_f32_e32 v16, v234, v16
	v_exp_f32_e32 v242, v17
	v_sub_f32_e32 v17, v48, v68
	v_add_f32_e32 v16, v235, v16
	v_exp_f32_e32 v243, v17
	v_add_f32_e32 v16, v236, v16
	v_add_f32_e32 v16, v237, v16
	v_add_f32_e32 v16, v242, v16
	v_add_f32_e32 v69, v243, v16
	v_cvt_pk_bf16_f32 v16, v56, v57
	v_cvt_pk_bf16_f32 v17, v58, v59
	v_cvt_pk_bf16_f32 v18, v60, v62
	v_cvt_pk_bf16_f32 v19, v63, v77
	v_cvt_pk_bf16_f32 v64, v78, v79
	v_cvt_pk_bf16_f32 v65, v82, v80
	v_cvt_pk_bf16_f32 v66, v76, v75
	v_cvt_pk_bf16_f32 v67, v74, v73
	v_cvt_pk_bf16_f32 v60, v32, v33
	v_cvt_pk_bf16_f32 v61, v34, v35
	v_cvt_pk_bf16_f32 v62, v36, v37
	v_cvt_pk_bf16_f32 v63, v38, v39
	v_cvt_pk_bf16_f32 v56, v40, v41
	v_cvt_pk_bf16_f32 v57, v42, v43
	v_cvt_pk_bf16_f32 v58, v44, v45
	v_cvt_pk_bf16_f32 v59, v46, v47
	v_cvt_pk_bf16_f32 v52, v83, v133
	v_cvt_pk_bf16_f32 v53, v143, v145
	v_cvt_pk_bf16_f32 v54, v20, v21
	v_cvt_pk_bf16_f32 v55, v22, v23
	v_cvt_pk_bf16_f32 v48, v24, v25
	v_cvt_pk_bf16_f32 v49, v26, v27
	v_cvt_pk_bf16_f32 v50, v28, v29
	v_cvt_pk_bf16_f32 v51, v30, v31
	v_cvt_pk_bf16_f32 v44, v0, v1
	v_cvt_pk_bf16_f32 v45, v2, v3
	v_cvt_pk_bf16_f32 v46, v4, v5
	v_cvt_pk_bf16_f32 v47, v6, v7
	v_cvt_pk_bf16_f32 v40, v8, v9
	v_cvt_pk_bf16_f32 v41, v10, v11
	v_cvt_pk_bf16_f32 v42, v12, v13
	v_cvt_pk_bf16_f32 v43, v14, v15
	v_cvt_pk_bf16_f32 v36, v147, v70
	ds_bpermute_b32 v70, v151, v69
	v_cvt_pk_bf16_f32 v37, v71, v72
	v_cvt_pk_bf16_f32 v38, v196, v197
	v_cvt_pk_bf16_f32 v39, v198, v199
	v_cvt_pk_bf16_f32 v32, v232, v233
	v_cvt_pk_bf16_f32 v33, v234, v235
	v_cvt_pk_bf16_f32 v34, v236, v237
	v_cvt_pk_bf16_f32 v35, v242, v243
	s_cbranch_vccnz .LBB0_1041
	s_ashr_i32 s19, s68, 3
	s_mul_hi_i32 s18, s19, 0x2aaaaaab
	s_lshr_b32 s21, s18, 31
	s_ashr_i32 s18, s18, 1
	s_add_i32 s18, s18, s21
	s_mul_i32 s21, s18, 12
	s_sub_i32 s21, s19, s21
	s_ashr_i32 s19, s18, 31
	s_lshl_b64 s[24:25], s[18:19], 23
	v_lshl_add_u64 v[0:1], v[134:135], 0, s[24:25]
	v_mad_i64_i32 v[0:1], s[18:19], s18, v200, v[0:1]
	s_lshl_b32 s18, s21, 6
	s_ashr_i32 s19, s18, 31
	v_lshl_add_u64 v[0:1], s[18:19], 1, v[0:1]
	s_lshl_b32 s18, s68, 8
	v_mov_b32_e32 v133, v81
	s_and_b32 s21, s18, 0x700
	v_mov_b32_e32 v88, v81
	v_mov_b32_e32 v89, v81
	v_lshl_add_u64 v[0:1], v[0:1], 0, v[132:133]
	v_add_u32_e32 v2, s21, v149
	v_mov_b32_e32 v90, v81
	v_mov_b32_e32 v91, v81
	v_mov_b64_e32 v[84:85], v[88:89]
	v_mad_i64_i32 v[0:1], s[18:19], v2, s40, v[0:1]
	v_cmp_gt_u32_e32 vcc, s44, v2
	v_mov_b64_e32 v[86:87], v[90:91]
	s_and_saveexec_b64 s[18:19], vcc
	s_cbranch_execz .LBB0_1018
	global_load_dwordx4 v[84:87], v[0:1], off
